# chain v4: LDS operand reads for the next step issued right after the step barrier in two groups, decay via one ds_read_b32 + DPP row broadcast multiply
# speedup vs baseline: 1.0275x; 1.0135x over previous
.LBB0_406:
	v_and_b32_e32 v1, 63, v0
	v_and_b32_e32 v2, 15, v1
	v_lshrrev_b32_e32 v3, 4, v1
	v_readfirstlane_b32 s6, v0
	s_lshr_b32 s7, s2, 4
	s_and_b32 s8, s2, 15
	s_nop 0
	s_lshr_b32 s6, s6, 6
	s_cmp_gt_u32 s6, 3
	s_cbranch_scc1 .Lser_loader
	v_lshrrev_b32_e32 v4, 1, v3
	v_and_b32_e32 v5, 1, v3
	v_lshlrev_b32_e32 v4, 8, v4
	v_lshl_add_u32 v4, v2, 4, v4
	v_lshl_add_u32 v4, v5, 3, v4
	s_lshl_b32 s12, s6, 4
	v_add_u32_e32 v5, s12, v2
	v_lshlrev_b32_e32 v6, 5, v5
	v_lshl_add_u32 v6, v3, 3, v6
	v_add_u32_e32 v6, 0x2400, v6
	v_lshlrev_b32_e32 v7, 9, v3
	v_lshl_add_u32 v7, v5, 1, v7
	v_add_u32_e32 v7, 0x2c00, v7
	v_lshrrev_b32_e32 v120, 2, v2
	v_lshlrev_b32_e32 v120, 6, v120
	v_lshl_add_u32 v120, v3, 4, v120
	v_and_b32_e32 v129, 3, v2
	v_lshl_add_u32 v120, v129, 2, v120
	v_add_u32_e32 v120, 0x3400, v120
	v_lshlrev_b32_e32 v116, 13, v3
	v_lshl_add_u32 v116, v5, 1, v116
	s_lshl_b32 s12, s7, 23
	s_lshl_b32 s13, s8, 7
	s_add_u32 s12, s12, s13
	s_add_u32 s12, s12, 0x14a08000
	v_add_u32_e32 v116, s12, v116
	v_mov_b32_e32 v117, 0
	s_mov_b64 s[14:15], 0x1000
	s_mov_b64 s[16:17], 0x8000
	v_lshl_add_u64 v[116:117], v[116:117], 0, s[70:71]
	v_lshl_add_u64 v[118:119], v[116:117], 0, s[14:15]
	v_mov_b32_e32 v8, 0
	v_mov_b32_e32 v9, 0
	v_mov_b32_e32 v10, 0
	v_mov_b32_e32 v11, 0
	v_mov_b32_e32 v12, 0
	v_mov_b32_e32 v13, 0
	v_mov_b32_e32 v14, 0
	v_mov_b32_e32 v15, 0
	v_mov_b32_e32 v16, 0
	v_mov_b32_e32 v17, 0
	v_mov_b32_e32 v18, 0
	v_mov_b32_e32 v19, 0
	v_mov_b32_e32 v20, 0
	v_mov_b32_e32 v21, 0
	v_mov_b32_e32 v22, 0
	v_mov_b32_e32 v23, 0
	v_mov_b32_e32 v24, 0
	v_mov_b32_e32 v25, 0
	v_mov_b32_e32 v26, 0
	v_mov_b32_e32 v27, 0
	v_mov_b32_e32 v28, 0
	v_mov_b32_e32 v29, 0
	v_mov_b32_e32 v30, 0
	v_mov_b32_e32 v31, 0
	s_mov_b32 s10, 0
	s_mov_b32 s11, 0
	s_barrier
	v_add_u32_e32 v121, s10, v4
	v_add_u32_e32 v126, s10, v6
	v_add_u32_e32 v127, s10, v7
	v_add_u32_e32 v128, s10, v120
	v_add_u32_e32 v122, 0x800, v121
	v_add_u32_e32 v123, 0x1000, v121
	v_add_u32_e32 v124, 0x1800, v121
	v_add_u32_e32 v125, 0x2000, v121
	ds_read_b64 v[48:49], v126
	ds_read2_b64 v[32:35], v121 offset1:64
	ds_read2_b64 v[36:39], v121 offset0:128 offset1:192
	ds_read2_b64 v[40:43], v122 offset1:64
	ds_read2_b64 v[44:47], v122 offset0:128 offset1:192
	ds_read_b32 v82, v128
	ds_read_u16 v133, v127
	ds_read_u16 v134, v127 offset:128
	ds_read_u16 v135, v127 offset:256
	ds_read_u16 v136, v127 offset:384
	ds_read2_b64 v[62:65], v123 offset1:64
	ds_read2_b64 v[66:69], v123 offset0:128 offset1:192
	ds_read2_b64 v[70:73], v124 offset1:64
	ds_read2_b64 v[74:77], v124 offset0:128 offset1:192
	ds_read2_b64 v[78:81], v125 offset1:64
	s_add_u32 s10, s10, 0x3800
	s_cmp_eq_u32 s10, 0x1c000
	s_cselect_b32 s10, 0, s10
	s_waitcnt lgkmcnt(9)
	v_lshlrev_b32_e32 v50, 16, v48
	v_and_b32_e32 v51, 0xffff0000, v48
	v_lshlrev_b32_e32 v52, 16, v49
	v_and_b32_e32 v53, 0xffff0000, v49
.Lser_chain_loop:
	s_nop 1
	v_mfma_f32_16x16x32_bf16 v[50:53], v[32:35], v[24:27], v[50:53]
	v_mfma_f32_16x16x32_bf16 v[50:53], v[36:39], v[28:31], v[50:53]
	s_barrier
	v_add_u32_e32 v121, s10, v4
	v_add_u32_e32 v126, s10, v6
	v_add_u32_e32 v127, s10, v7
	v_add_u32_e32 v128, s10, v120
	v_add_u32_e32 v122, 0x800, v121
	v_add_u32_e32 v123, 0x1000, v121
	v_add_u32_e32 v124, 0x1800, v121
	v_add_u32_e32 v125, 0x2000, v121
	ds_read_b64 v[140:141], v126
	ds_read2_b64 v[142:145], v121 offset1:64
	ds_read2_b64 v[146:149], v121 offset0:128 offset1:192
	ds_read2_b64 v[150:153], v122 offset1:64
	ds_read2_b64 v[154:157], v122 offset0:128 offset1:192
	ds_read_b32 v158, v128
	v_mfma_f32_16x16x32_bf16 v[54:57], v[40:43], v[24:27], 0
	v_mfma_f32_16x16x32_bf16 v[54:57], v[44:47], v[28:31], v[54:57]
	v_mul_f32_dpp v98, v82, v8 row_newbcast:0 row_mask:0xf bank_mask:0xf
	v_mul_f32_dpp v99, v82, v9 row_newbcast:1 row_mask:0xf bank_mask:0xf
	v_mul_f32_dpp v100, v82, v10 row_newbcast:2 row_mask:0xf bank_mask:0xf
	v_mul_f32_dpp v101, v82, v11 row_newbcast:3 row_mask:0xf bank_mask:0xf
	v_mul_f32_dpp v102, v82, v12 row_newbcast:4 row_mask:0xf bank_mask:0xf
	v_mul_f32_dpp v103, v82, v13 row_newbcast:5 row_mask:0xf bank_mask:0xf
	v_mul_f32_dpp v104, v82, v14 row_newbcast:6 row_mask:0xf bank_mask:0xf
	v_mul_f32_dpp v105, v82, v15 row_newbcast:7 row_mask:0xf bank_mask:0xf
	v_mul_f32_dpp v106, v82, v16 row_newbcast:8 row_mask:0xf bank_mask:0xf
	v_mul_f32_dpp v107, v82, v17 row_newbcast:9 row_mask:0xf bank_mask:0xf
	v_mul_f32_dpp v108, v82, v18 row_newbcast:10 row_mask:0xf bank_mask:0xf
	v_mul_f32_dpp v109, v82, v19 row_newbcast:11 row_mask:0xf bank_mask:0xf
	v_mul_f32_dpp v110, v82, v20 row_newbcast:12 row_mask:0xf bank_mask:0xf
	v_mul_f32_dpp v111, v82, v21 row_newbcast:13 row_mask:0xf bank_mask:0xf
	v_mul_f32_dpp v112, v82, v22 row_newbcast:14 row_mask:0xf bank_mask:0xf
	v_mul_f32_dpp v113, v82, v23 row_newbcast:15 row_mask:0xf bank_mask:0xf
	v_cvt_pk_bf16_f32 v58, v50, v51
	v_cvt_pk_bf16_f32 v59, v52, v53
	s_waitcnt lgkmcnt(6)
	v_lshl_or_b32 v60, v134, 16, v133
	v_lshl_or_b32 v61, v136, 16, v135
	s_nop 1
	v_mfma_f32_16x16x32_bf16 v[8:11], v[62:65], v[58:61], v[98:101]
	v_mfma_f32_16x16x32_bf16 v[12:15], v[66:69], v[58:61], v[102:105]
	v_mfma_f32_16x16x32_bf16 v[16:19], v[70:73], v[58:61], v[106:109]
	v_mfma_f32_16x16x32_bf16 v[20:23], v[74:77], v[58:61], v[110:113]
	v_mfma_f32_16x16x32_bf16 v[54:57], v[78:81], v[58:61], v[54:57]
	ds_read_u16 v174, v127
	ds_read_u16 v175, v127 offset:128
	ds_read_u16 v176, v127 offset:256
	ds_read_u16 v177, v127 offset:384
	ds_read2_b64 v[184:187], v123 offset1:64
	ds_read2_b64 v[188:191], v123 offset0:128 offset1:192
	ds_read2_b64 v[192:195], v124 offset1:64
	ds_read2_b64 v[196:199], v124 offset0:128 offset1:192
	ds_read2_b64 v[200:203], v125 offset1:64
	s_add_u32 s10, s10, 0x3800
	s_cmp_eq_u32 s10, 0x1c000
	s_cselect_b32 s10, 0, s10
	v_cvt_pk_bf16_f32 v24, v8, v9
	v_cvt_pk_bf16_f32 v25, v10, v11
	v_cvt_pk_bf16_f32 v26, v12, v13
	v_cvt_pk_bf16_f32 v27, v14, v15
	v_cvt_pk_bf16_f32 v28, v16, v17
	v_cvt_pk_bf16_f32 v29, v18, v19
	v_cvt_pk_bf16_f32 v30, v20, v21
	v_cvt_pk_bf16_f32 v31, v22, v23
	v_cvt_pk_bf16_f32 v114, v54, v54
	v_cvt_pk_bf16_f32 v115, v55, v55
	v_cvt_pk_bf16_f32 v131, v56, v56
	v_cvt_pk_bf16_f32 v132, v57, v57
	global_store_short v[116:117], v114, off
	global_store_short v[116:117], v115, off offset:2048
	global_store_short v[118:119], v131, off
	global_store_short v[118:119], v132, off offset:2048
	v_lshl_add_u64 v[116:117], v[116:117], 0, s[16:17]
	v_lshl_add_u64 v[118:119], v[118:119], 0, s[16:17]
	s_waitcnt lgkmcnt(9)
	v_lshlrev_b32_e32 v50, 16, v140
	v_and_b32_e32 v51, 0xffff0000, v140
	v_lshlrev_b32_e32 v52, 16, v141
	v_and_b32_e32 v53, 0xffff0000, v141
	s_nop 1
	v_mfma_f32_16x16x32_bf16 v[50:53], v[142:145], v[24:27], v[50:53]
	v_mfma_f32_16x16x32_bf16 v[50:53], v[146:149], v[28:31], v[50:53]
	s_barrier
	v_add_u32_e32 v121, s10, v4
	v_add_u32_e32 v126, s10, v6
	v_add_u32_e32 v127, s10, v7
	v_add_u32_e32 v128, s10, v120
	v_add_u32_e32 v122, 0x800, v121
	v_add_u32_e32 v123, 0x1000, v121
	v_add_u32_e32 v124, 0x1800, v121
	v_add_u32_e32 v125, 0x2000, v121
	ds_read_b64 v[48:49], v126
	ds_read2_b64 v[32:35], v121 offset1:64
	ds_read2_b64 v[36:39], v121 offset0:128 offset1:192
	ds_read2_b64 v[40:43], v122 offset1:64
	ds_read2_b64 v[44:47], v122 offset0:128 offset1:192
	ds_read_b32 v82, v128
	v_mfma_f32_16x16x32_bf16 v[54:57], v[150:153], v[24:27], 0
	v_mfma_f32_16x16x32_bf16 v[54:57], v[154:157], v[28:31], v[54:57]
	v_mul_f32_dpp v98, v158, v8 row_newbcast:0 row_mask:0xf bank_mask:0xf
	v_mul_f32_dpp v99, v158, v9 row_newbcast:1 row_mask:0xf bank_mask:0xf
	v_mul_f32_dpp v100, v158, v10 row_newbcast:2 row_mask:0xf bank_mask:0xf
	v_mul_f32_dpp v101, v158, v11 row_newbcast:3 row_mask:0xf bank_mask:0xf
	v_mul_f32_dpp v102, v158, v12 row_newbcast:4 row_mask:0xf bank_mask:0xf
	v_mul_f32_dpp v103, v158, v13 row_newbcast:5 row_mask:0xf bank_mask:0xf
	v_mul_f32_dpp v104, v158, v14 row_newbcast:6 row_mask:0xf bank_mask:0xf
	v_mul_f32_dpp v105, v158, v15 row_newbcast:7 row_mask:0xf bank_mask:0xf
	v_mul_f32_dpp v106, v158, v16 row_newbcast:8 row_mask:0xf bank_mask:0xf
	v_mul_f32_dpp v107, v158, v17 row_newbcast:9 row_mask:0xf bank_mask:0xf
	v_mul_f32_dpp v108, v158, v18 row_newbcast:10 row_mask:0xf bank_mask:0xf
	v_mul_f32_dpp v109, v158, v19 row_newbcast:11 row_mask:0xf bank_mask:0xf
	v_mul_f32_dpp v110, v158, v20 row_newbcast:12 row_mask:0xf bank_mask:0xf
	v_mul_f32_dpp v111, v158, v21 row_newbcast:13 row_mask:0xf bank_mask:0xf
	v_mul_f32_dpp v112, v158, v22 row_newbcast:14 row_mask:0xf bank_mask:0xf
	v_mul_f32_dpp v113, v158, v23 row_newbcast:15 row_mask:0xf bank_mask:0xf
	v_cvt_pk_bf16_f32 v180, v50, v51
	v_cvt_pk_bf16_f32 v181, v52, v53
	s_waitcnt lgkmcnt(6)
	v_lshl_or_b32 v182, v175, 16, v174
	v_lshl_or_b32 v183, v177, 16, v176
	s_nop 1
	v_mfma_f32_16x16x32_bf16 v[8:11], v[184:187], v[180:183], v[98:101]
	v_mfma_f32_16x16x32_bf16 v[12:15], v[188:191], v[180:183], v[102:105]
	v_mfma_f32_16x16x32_bf16 v[16:19], v[192:195], v[180:183], v[106:109]
	v_mfma_f32_16x16x32_bf16 v[20:23], v[196:199], v[180:183], v[110:113]
	v_mfma_f32_16x16x32_bf16 v[54:57], v[200:203], v[180:183], v[54:57]
	ds_read_u16 v133, v127
	ds_read_u16 v134, v127 offset:128
	ds_read_u16 v135, v127 offset:256
	ds_read_u16 v136, v127 offset:384
	ds_read2_b64 v[62:65], v123 offset1:64
	ds_read2_b64 v[66:69], v123 offset0:128 offset1:192
	ds_read2_b64 v[70:73], v124 offset1:64
	ds_read2_b64 v[74:77], v124 offset0:128 offset1:192
	ds_read2_b64 v[78:81], v125 offset1:64
	s_add_u32 s10, s10, 0x3800
	s_cmp_eq_u32 s10, 0x1c000
	s_cselect_b32 s10, 0, s10
	v_cvt_pk_bf16_f32 v24, v8, v9
	v_cvt_pk_bf16_f32 v25, v10, v11
	v_cvt_pk_bf16_f32 v26, v12, v13
	v_cvt_pk_bf16_f32 v27, v14, v15
	v_cvt_pk_bf16_f32 v28, v16, v17
	v_cvt_pk_bf16_f32 v29, v18, v19
	v_cvt_pk_bf16_f32 v30, v20, v21
	v_cvt_pk_bf16_f32 v31, v22, v23
	v_cvt_pk_bf16_f32 v114, v54, v54
	v_cvt_pk_bf16_f32 v115, v55, v55
	v_cvt_pk_bf16_f32 v131, v56, v56
	v_cvt_pk_bf16_f32 v132, v57, v57
	global_store_short v[116:117], v114, off
	global_store_short v[116:117], v115, off offset:2048
	global_store_short v[118:119], v131, off
	global_store_short v[118:119], v132, off offset:2048
	v_lshl_add_u64 v[116:117], v[116:117], 0, s[16:17]
	v_lshl_add_u64 v[118:119], v[118:119], 0, s[16:17]
	s_waitcnt lgkmcnt(9)
	v_lshlrev_b32_e32 v50, 16, v48
	v_and_b32_e32 v51, 0xffff0000, v48
	v_lshlrev_b32_e32 v52, 16, v49
	v_and_b32_e32 v53, 0xffff0000, v49
	s_add_u32 s11, s11, 2
	s_cmp_lt_u32 s11, 0x100
	s_cbranch_scc1 .Lser_chain_loop
	s_waitcnt lgkmcnt(0)
	s_branch .Lser_exit
